# hand-written LDS-free pipelined f32->bf16 weight conversion loop in FFN1-gu and in-proj tails (replaces compiled convert_items with vmcnt(0) stall)
# speedup vs baseline: 1.0033x; 1.0033x over previous
.LBB0_511:
	v_readlane_b32 s0, v234, 12
	v_writelane_b32 v233, s52, 12
	s_abs_i32 s52, s0
	v_cvt_f32_u32_e32 v0, s52
	s_sub_i32 s0, 0, s52
	v_readlane_b32 s1, v234, 13
	v_writelane_b32 v233, s50, 13
	v_rcp_iflag_f32_e32 v0, v0
	s_nop 0
	v_writelane_b32 v233, s51, 14
	v_mul_f32_e32 v0, 0x4f7ffffe, v0
	v_cvt_u32_f32_e32 v0, v0
	s_nop 0
	v_readfirstlane_b32 s53, v0
	s_mul_i32 s0, s0, s53
	s_mul_hi_u32 s0, s53, s0
	s_add_i32 s53, s53, s0
	s_mul_hi_u32 s0, s53, 0x5ac
	s_mul_i32 s0, s0, s52
	s_sub_i32 s0, 0x5ac, s0
	s_sub_i32 s1, s0, s52
	s_cmp_ge_u32 s0, s52
	s_cselect_b32 s0, s1, s0
	s_sub_i32 s1, s0, s52
	s_cmp_ge_u32 s0, s52
	s_cselect_b32 s5, s1, s0
	s_cmp_eq_u32 s5, 0
	s_cselect_b64 s[0:1], -1, 0
	s_cmp_lt_i32 s4, s5
	s_cselect_b64 s[2:3], -1, 0
	s_or_b64 s[0:1], s[0:1], s[2:3]
	s_and_b64 vcc, exec, s[0:1]
	s_cbranch_vccnz .LBB0_931
	v_readlane_b32 s2, v234, 14
	v_readlane_b32 s3, v234, 12
	v_readfirstlane_b32 s0, v183
	s_sub_i32 s2, s2, s5
	s_sub_i32 s3, s3, s5
	s_lshl_b32 s2, s2, 3
	s_lshr_b32 s0, s0, 6
	s_add_i32 s4, s2, s0
	s_lshl_b32 s33, s3, 3
	s_cmp_ge_u32 s4, 0x1600
	s_cbranch_scc1 .LBB0_931
	v_readlane_b32 s30, v234, 2
	v_readlane_b32 s31, v234, 3
	v_and_b32_e32 v176, 7, v183
	v_bfe_u32 v185, v183, 3, 3
	v_lshlrev_b32_e32 v177, 4, v185
	v_lshlrev_b32_e32 v186, 4, v176
	v_lshlrev_b32_e32 v184, 5, v176
	s_cmp_lt_u32 s4, 0x1600
	s_cbranch_scc1 .Lcv1_p0_go
	s_mov_b32 s22, 0
	s_branch .Lcv1_p0_end
.Lcv1_p0_go:
	s_cmp_lt_u32 s4, 0xb00
	s_cbranch_scc0 .Lcv1_p0_seg1
	s_sub_u32 s34, s4, 0x0
	s_lshr_b32 s39, s34, 5
	s_and_b32 s40, s34, 31
	v_readlane_b32 s0, v234, 44
	v_readlane_b32 s1, v234, 45
	s_mul_i32 s2, s39, 0x80000
	s_lshl_b32 s3, s40, 8
	s_add_u32 s2, s2, s3
	s_add_u32 s0, s0, s2
	s_addc_u32 s1, s1, 0
	s_mov_b32 s41, 0x2000
	s_mov_b32 s42, 0x10000
	s_mul_i32 s2, s40, 0xb0000
	s_lshl_b32 s3, s39, 7
	s_add_u32 s2, s2, s3
	s_add_u32 s2, s2, 0x2e00000
	s_add_u32 s16, s30, s2
	s_addc_u32 s17, s31, 0
	s_mov_b32 s20, 0x2c00
	s_mov_b32 s21, 0xb000
	s_mov_b32 s22, 16
	s_branch .Lcv1_p0_ld
.Lcv1_p0_seg1:
	s_sub_u32 s34, s4, 0xb00
	s_mul_i32 s39, s34, 5958
	s_lshr_b32 s39, s39, 19
	s_mul_i32 s40, s39, 88
	s_sub_u32 s40, s34, s40
	v_readlane_b32 s0, v234, 4
	v_readlane_b32 s1, v234, 5
	s_mul_i32 s2, s39, 0x160000
	s_lshl_b32 s3, s40, 8
	s_add_u32 s2, s2, s3
	s_add_u32 s0, s0, s2
	s_addc_u32 s1, s1, 0
	s_mov_b32 s41, 0x5800
	s_mov_b32 s42, 0x2c000
	s_lshr_b32 s2, s40, 1
	s_lshl_b32 s2, s2, 8
	s_and_b32 s3, s40, 1
	s_lshl_b32 s3, s3, 6
	s_add_u32 s2, s2, s3
	s_mul_i32 s2, s2, 0x1000
	s_lshl_b32 s3, s39, 7
	s_add_u32 s2, s2, s3
	s_add_u32 s2, s2, 0x8700000
	s_add_u32 s16, s30, s2
	s_addc_u32 s17, s31, 0
	s_mov_b32 s20, 0x1000
	s_mov_b32 s21, 0x4000
	v_readlane_b32 s8, v233, 6
	v_readlane_b32 s9, v233, 7
	s_lshl_b32 s3, s39, 8
	s_mov_b32 s22, 18
	s_nop 0
	s_add_u32 s8, s8, s3
	s_addc_u32 s9, s9, 0
.Lcv1_p0_ld:
	v_mad_u32_u24 v178, v176, s42, v177
	global_load_dwordx4 v[0:3], v178, s[0:1] nt
	global_load_dwordx4 v[4:7], v178, s[0:1] offset:128 nt
	s_add_u32 s0, s0, s41
	s_addc_u32 s1, s1, 0
	global_load_dwordx4 v[8:11], v178, s[0:1] nt
	global_load_dwordx4 v[12:15], v178, s[0:1] offset:128 nt
	s_add_u32 s0, s0, s41
	s_addc_u32 s1, s1, 0
	global_load_dwordx4 v[16:19], v178, s[0:1] nt
	global_load_dwordx4 v[20:23], v178, s[0:1] offset:128 nt
	s_add_u32 s0, s0, s41
	s_addc_u32 s1, s1, 0
	global_load_dwordx4 v[24:27], v178, s[0:1] nt
	global_load_dwordx4 v[28:31], v178, s[0:1] offset:128 nt
	s_add_u32 s0, s0, s41
	s_addc_u32 s1, s1, 0
	global_load_dwordx4 v[32:35], v178, s[0:1] nt
	global_load_dwordx4 v[36:39], v178, s[0:1] offset:128 nt
	s_add_u32 s0, s0, s41
	s_addc_u32 s1, s1, 0
	global_load_dwordx4 v[40:43], v178, s[0:1] nt
	global_load_dwordx4 v[44:47], v178, s[0:1] offset:128 nt
	s_add_u32 s0, s0, s41
	s_addc_u32 s1, s1, 0
	global_load_dwordx4 v[48:51], v178, s[0:1] nt
	global_load_dwordx4 v[52:55], v178, s[0:1] offset:128 nt
	s_add_u32 s0, s0, s41
	s_addc_u32 s1, s1, 0
	global_load_dwordx4 v[56:59], v178, s[0:1] nt
	global_load_dwordx4 v[60:63], v178, s[0:1] offset:128 nt
	s_cmp_eq_u32 s22, 18
	s_cbranch_scc0 .Lcv1_p0_nokw
	global_load_dwordx4 v[128:131], v184, s[8:9]
	global_load_dwordx4 v[132:135], v184, s[8:9] offset:16
	s_branch .Lcv1_p0_kwd
.Lcv1_p0_nokw:
	v_mov_b32_e32 v128, 1.0
	v_mov_b32_e32 v129, 1.0
	v_mov_b32_e32 v130, 1.0
	v_mov_b32_e32 v131, 1.0
	v_mov_b32_e32 v132, 1.0
	v_mov_b32_e32 v133, 1.0
	v_mov_b32_e32 v134, 1.0
	v_mov_b32_e32 v135, 1.0
.Lcv1_p0_kwd:
	s_add_u32 s4, s4, s33
.Lcv1_p0_end:
	s_cmp_lt_u32 s4, 0x1600
	s_cbranch_scc1 .Lcv1_p1_go
	s_mov_b32 s28, 0
	s_branch .Lcv1_p1_end
.Lcv1_p1_go:
	s_cmp_lt_u32 s4, 0xb00
	s_cbranch_scc0 .Lcv1_p1_seg1
	s_sub_u32 s34, s4, 0x0
	s_lshr_b32 s39, s34, 5
	s_and_b32 s40, s34, 31
	v_readlane_b32 s0, v234, 44
	v_readlane_b32 s1, v234, 45
	s_mul_i32 s2, s39, 0x80000
	s_lshl_b32 s3, s40, 8
	s_add_u32 s2, s2, s3
	s_add_u32 s0, s0, s2
	s_addc_u32 s1, s1, 0
	s_mov_b32 s41, 0x2000
	s_mov_b32 s42, 0x10000
	s_mul_i32 s2, s40, 0xb0000
	s_lshl_b32 s3, s39, 7
	s_add_u32 s2, s2, s3
	s_add_u32 s2, s2, 0x2e00000
	s_add_u32 s24, s30, s2
	s_addc_u32 s25, s31, 0
	s_mov_b32 s26, 0x2c00
	s_mov_b32 s27, 0xb000
	s_mov_b32 s28, 16
	s_branch .Lcv1_p1_ld
.Lcv1_p1_seg1:
	s_sub_u32 s34, s4, 0xb00
	s_mul_i32 s39, s34, 5958
	s_lshr_b32 s39, s39, 19
	s_mul_i32 s40, s39, 88
	s_sub_u32 s40, s34, s40
	v_readlane_b32 s0, v234, 4
	v_readlane_b32 s1, v234, 5
	s_mul_i32 s2, s39, 0x160000
	s_lshl_b32 s3, s40, 8
	s_add_u32 s2, s2, s3
	s_add_u32 s0, s0, s2
	s_addc_u32 s1, s1, 0
	s_mov_b32 s41, 0x5800
	s_mov_b32 s42, 0x2c000
	s_lshr_b32 s2, s40, 1
	s_lshl_b32 s2, s2, 8
	s_and_b32 s3, s40, 1
	s_lshl_b32 s3, s3, 6
	s_add_u32 s2, s2, s3
	s_mul_i32 s2, s2, 0x1000
	s_lshl_b32 s3, s39, 7
	s_add_u32 s2, s2, s3
	s_add_u32 s2, s2, 0x8700000
	s_add_u32 s24, s30, s2
	s_addc_u32 s25, s31, 0
	s_mov_b32 s26, 0x1000
	s_mov_b32 s27, 0x4000
	v_readlane_b32 s8, v233, 6
	v_readlane_b32 s9, v233, 7
	s_lshl_b32 s3, s39, 8
	s_mov_b32 s28, 18
	s_nop 0
	s_add_u32 s8, s8, s3
	s_addc_u32 s9, s9, 0
.Lcv1_p1_ld:
	v_mad_u32_u24 v178, v176, s42, v177
	global_load_dwordx4 v[64:67], v178, s[0:1] nt
	global_load_dwordx4 v[68:71], v178, s[0:1] offset:128 nt
	s_add_u32 s0, s0, s41
	s_addc_u32 s1, s1, 0
	global_load_dwordx4 v[72:75], v178, s[0:1] nt
	global_load_dwordx4 v[76:79], v178, s[0:1] offset:128 nt
	s_add_u32 s0, s0, s41
	s_addc_u32 s1, s1, 0
	global_load_dwordx4 v[80:83], v178, s[0:1] nt
	global_load_dwordx4 v[84:87], v178, s[0:1] offset:128 nt
	s_add_u32 s0, s0, s41
	s_addc_u32 s1, s1, 0
	global_load_dwordx4 v[88:91], v178, s[0:1] nt
	global_load_dwordx4 v[92:95], v178, s[0:1] offset:128 nt
	s_add_u32 s0, s0, s41
	s_addc_u32 s1, s1, 0
	global_load_dwordx4 v[96:99], v178, s[0:1] nt
	global_load_dwordx4 v[100:103], v178, s[0:1] offset:128 nt
	s_add_u32 s0, s0, s41
	s_addc_u32 s1, s1, 0
	global_load_dwordx4 v[104:107], v178, s[0:1] nt
	global_load_dwordx4 v[108:111], v178, s[0:1] offset:128 nt
	s_add_u32 s0, s0, s41
	s_addc_u32 s1, s1, 0
	global_load_dwordx4 v[112:115], v178, s[0:1] nt
	global_load_dwordx4 v[116:119], v178, s[0:1] offset:128 nt
	s_add_u32 s0, s0, s41
	s_addc_u32 s1, s1, 0
	global_load_dwordx4 v[120:123], v178, s[0:1] nt
	global_load_dwordx4 v[124:127], v178, s[0:1] offset:128 nt
	s_cmp_eq_u32 s28, 18
	s_cbranch_scc0 .Lcv1_p1_nokw
	global_load_dwordx4 v[136:139], v184, s[8:9]
	global_load_dwordx4 v[140:143], v184, s[8:9] offset:16
	s_branch .Lcv1_p1_kwd
.Lcv1_p1_nokw:
	v_mov_b32_e32 v136, 1.0
	v_mov_b32_e32 v137, 1.0
	v_mov_b32_e32 v138, 1.0
	v_mov_b32_e32 v139, 1.0
	v_mov_b32_e32 v140, 1.0
	v_mov_b32_e32 v141, 1.0
	v_mov_b32_e32 v142, 1.0
	v_mov_b32_e32 v143, 1.0

.Lcv1_p1_end:
	s_cmp_eq_u32 s28, 18
	s_cbranch_scc1 .Lcv1_pw_w18
	s_cmp_eq_u32 s28, 16
	s_cbranch_scc1 .Lcv1_pw_w16
	s_waitcnt vmcnt(0)
	s_branch .Lcv1_pw_wd
.Lcv1_pw_w18:
	s_waitcnt vmcnt(18)
	s_branch .Lcv1_pw_wd
.Lcv1_pw_w16:
	s_waitcnt vmcnt(16)
.Lcv1_pw_wd:
.Lcv1_loop:
	v_mad_u32_u24 v179, v185, s21, v186
	v_pk_mul_f32 v[0:1], v[0:1], v[128:129] op_sel_hi:[1,0]
	v_pk_mul_f32 v[2:3], v[2:3], v[128:129] op_sel_hi:[1,0]
	v_pk_mul_f32 v[4:5], v[4:5], v[128:129] op_sel_hi:[1,0]
	v_pk_mul_f32 v[6:7], v[6:7], v[128:129] op_sel_hi:[1,0]
	v_pk_mul_f32 v[8:9], v[8:9], v[128:129] op_sel:[0,1]
	v_pk_mul_f32 v[10:11], v[10:11], v[128:129] op_sel:[0,1]
	v_pk_mul_f32 v[12:13], v[12:13], v[128:129] op_sel:[0,1]
	v_pk_mul_f32 v[14:15], v[14:15], v[128:129] op_sel:[0,1]
	v_pk_mul_f32 v[16:17], v[16:17], v[130:131] op_sel_hi:[1,0]
	v_pk_mul_f32 v[18:19], v[18:19], v[130:131] op_sel_hi:[1,0]
	v_pk_mul_f32 v[20:21], v[20:21], v[130:131] op_sel_hi:[1,0]
	v_pk_mul_f32 v[22:23], v[22:23], v[130:131] op_sel_hi:[1,0]
	v_pk_mul_f32 v[24:25], v[24:25], v[130:131] op_sel:[0,1]
	v_pk_mul_f32 v[26:27], v[26:27], v[130:131] op_sel:[0,1]
	v_pk_mul_f32 v[28:29], v[28:29], v[130:131] op_sel:[0,1]
	v_pk_mul_f32 v[30:31], v[30:31], v[130:131] op_sel:[0,1]
	v_pk_mul_f32 v[32:33], v[32:33], v[132:133] op_sel_hi:[1,0]
	v_pk_mul_f32 v[34:35], v[34:35], v[132:133] op_sel_hi:[1,0]
	v_pk_mul_f32 v[36:37], v[36:37], v[132:133] op_sel_hi:[1,0]
	v_pk_mul_f32 v[38:39], v[38:39], v[132:133] op_sel_hi:[1,0]
	v_pk_mul_f32 v[40:41], v[40:41], v[132:133] op_sel:[0,1]
	v_pk_mul_f32 v[42:43], v[42:43], v[132:133] op_sel:[0,1]
	v_pk_mul_f32 v[44:45], v[44:45], v[132:133] op_sel:[0,1]
	v_pk_mul_f32 v[46:47], v[46:47], v[132:133] op_sel:[0,1]
	v_pk_mul_f32 v[48:49], v[48:49], v[134:135] op_sel_hi:[1,0]
	v_pk_mul_f32 v[50:51], v[50:51], v[134:135] op_sel_hi:[1,0]
	v_pk_mul_f32 v[52:53], v[52:53], v[134:135] op_sel_hi:[1,0]
	v_pk_mul_f32 v[54:55], v[54:55], v[134:135] op_sel_hi:[1,0]
	v_pk_mul_f32 v[56:57], v[56:57], v[134:135] op_sel:[0,1]
	v_pk_mul_f32 v[58:59], v[58:59], v[134:135] op_sel:[0,1]
	v_pk_mul_f32 v[60:61], v[60:61], v[134:135] op_sel:[0,1]
	v_pk_mul_f32 v[62:63], v[62:63], v[134:135] op_sel:[0,1]
	v_cvt_pk_bf16_f32 v144, v0, v8
	v_cvt_pk_bf16_f32 v145, v16, v24
	v_cvt_pk_bf16_f32 v146, v32, v40
	v_cvt_pk_bf16_f32 v147, v48, v56
	global_store_dwordx4 v179, v[144:147], s[16:17]
	v_cvt_pk_bf16_f32 v148, v1, v9
	v_cvt_pk_bf16_f32 v149, v17, v25
	v_cvt_pk_bf16_f32 v150, v33, v41
	v_cvt_pk_bf16_f32 v151, v49, v57
	s_add_u32 s16, s16, s20
	s_addc_u32 s17, s17, 0
	global_store_dwordx4 v179, v[148:151], s[16:17]
	v_cvt_pk_bf16_f32 v152, v2, v10
	v_cvt_pk_bf16_f32 v153, v18, v26
	v_cvt_pk_bf16_f32 v154, v34, v42
	v_cvt_pk_bf16_f32 v155, v50, v58
	s_add_u32 s16, s16, s20
	s_addc_u32 s17, s17, 0
	global_store_dwordx4 v179, v[152:155], s[16:17]
	v_cvt_pk_bf16_f32 v156, v3, v11
	v_cvt_pk_bf16_f32 v157, v19, v27
	v_cvt_pk_bf16_f32 v158, v35, v43
	v_cvt_pk_bf16_f32 v159, v51, v59
	s_add_u32 s16, s16, s20
	s_addc_u32 s17, s17, 0
	global_store_dwordx4 v179, v[156:159], s[16:17]
	v_cvt_pk_bf16_f32 v160, v4, v12
	v_cvt_pk_bf16_f32 v161, v20, v28
	v_cvt_pk_bf16_f32 v162, v36, v44
	v_cvt_pk_bf16_f32 v163, v52, v60
	s_mul_i32 s2, s20, 29
	s_add_u32 s16, s16, s2
	s_addc_u32 s17, s17, 0
	global_store_dwordx4 v179, v[160:163], s[16:17]
	v_cvt_pk_bf16_f32 v164, v5, v13
	v_cvt_pk_bf16_f32 v165, v21, v29
	v_cvt_pk_bf16_f32 v166, v37, v45
	v_cvt_pk_bf16_f32 v167, v53, v61
	s_add_u32 s16, s16, s20
	s_addc_u32 s17, s17, 0
	global_store_dwordx4 v179, v[164:167], s[16:17]
	v_cvt_pk_bf16_f32 v168, v6, v14
	v_cvt_pk_bf16_f32 v169, v22, v30
	v_cvt_pk_bf16_f32 v170, v38, v46
	v_cvt_pk_bf16_f32 v171, v54, v62
	s_add_u32 s16, s16, s20
	s_addc_u32 s17, s17, 0
	global_store_dwordx4 v179, v[168:171], s[16:17]
	v_cvt_pk_bf16_f32 v172, v7, v15
	v_cvt_pk_bf16_f32 v173, v23, v31
	v_cvt_pk_bf16_f32 v174, v39, v47
	v_cvt_pk_bf16_f32 v175, v55, v63
	s_add_u32 s16, s16, s20
	s_addc_u32 s17, s17, 0
	global_store_dwordx4 v179, v[172:175], s[16:17]
	s_cmp_lt_u32 s4, 0x1600
	s_cbranch_scc1 .Lcv1_la_go
	s_mov_b32 s22, 0
	s_branch .Lcv1_la_end

.Lcv1_la_end:
	s_cmp_eq_u32 s28, 0
	s_cbranch_scc1 .Lcv1_done
	s_cmp_eq_u32 s22, 18
	s_cbranch_scc1 .Lcv1_wb_w18
	s_cmp_eq_u32 s22, 16
	s_cbranch_scc1 .Lcv1_wb_w16
	s_waitcnt vmcnt(8)
	s_branch .Lcv1_wb_wd
.Lcv1_wb_w18:
	s_waitcnt vmcnt(26)
	s_branch .Lcv1_wb_wd
.Lcv1_wb_w16:
	s_waitcnt vmcnt(24)
.Lcv1_wb_wd:
	v_mad_u32_u24 v179, v185, s27, v186
	v_pk_mul_f32 v[64:65], v[64:65], v[136:137] op_sel_hi:[1,0]
	v_pk_mul_f32 v[66:67], v[66:67], v[136:137] op_sel_hi:[1,0]
	v_pk_mul_f32 v[68:69], v[68:69], v[136:137] op_sel_hi:[1,0]
	v_pk_mul_f32 v[70:71], v[70:71], v[136:137] op_sel_hi:[1,0]
	v_pk_mul_f32 v[72:73], v[72:73], v[136:137] op_sel:[0,1]
	v_pk_mul_f32 v[74:75], v[74:75], v[136:137] op_sel:[0,1]
	v_pk_mul_f32 v[76:77], v[76:77], v[136:137] op_sel:[0,1]
	v_pk_mul_f32 v[78:79], v[78:79], v[136:137] op_sel:[0,1]
	v_pk_mul_f32 v[80:81], v[80:81], v[138:139] op_sel_hi:[1,0]
	v_pk_mul_f32 v[82:83], v[82:83], v[138:139] op_sel_hi:[1,0]
	v_pk_mul_f32 v[84:85], v[84:85], v[138:139] op_sel_hi:[1,0]
	v_pk_mul_f32 v[86:87], v[86:87], v[138:139] op_sel_hi:[1,0]
	v_pk_mul_f32 v[88:89], v[88:89], v[138:139] op_sel:[0,1]
	v_pk_mul_f32 v[90:91], v[90:91], v[138:139] op_sel:[0,1]
	v_pk_mul_f32 v[92:93], v[92:93], v[138:139] op_sel:[0,1]
	v_pk_mul_f32 v[94:95], v[94:95], v[138:139] op_sel:[0,1]
	v_pk_mul_f32 v[96:97], v[96:97], v[140:141] op_sel_hi:[1,0]
	v_pk_mul_f32 v[98:99], v[98:99], v[140:141] op_sel_hi:[1,0]
	v_pk_mul_f32 v[100:101], v[100:101], v[140:141] op_sel_hi:[1,0]
	v_pk_mul_f32 v[102:103], v[102:103], v[140:141] op_sel_hi:[1,0]
	v_pk_mul_f32 v[104:105], v[104:105], v[140:141] op_sel:[0,1]
	v_pk_mul_f32 v[106:107], v[106:107], v[140:141] op_sel:[0,1]
	v_pk_mul_f32 v[108:109], v[108:109], v[140:141] op_sel:[0,1]
	v_pk_mul_f32 v[110:111], v[110:111], v[140:141] op_sel:[0,1]
	v_pk_mul_f32 v[112:113], v[112:113], v[142:143] op_sel_hi:[1,0]
	v_pk_mul_f32 v[114:115], v[114:115], v[142:143] op_sel_hi:[1,0]
	v_pk_mul_f32 v[116:117], v[116:117], v[142:143] op_sel_hi:[1,0]
	v_pk_mul_f32 v[118:119], v[118:119], v[142:143] op_sel_hi:[1,0]
	v_pk_mul_f32 v[120:121], v[120:121], v[142:143] op_sel:[0,1]
	v_pk_mul_f32 v[122:123], v[122:123], v[142:143] op_sel:[0,1]
	v_pk_mul_f32 v[124:125], v[124:125], v[142:143] op_sel:[0,1]
	v_pk_mul_f32 v[126:127], v[126:127], v[142:143] op_sel:[0,1]
	v_cvt_pk_bf16_f32 v144, v64, v72
	v_cvt_pk_bf16_f32 v145, v80, v88
	v_cvt_pk_bf16_f32 v146, v96, v104
	v_cvt_pk_bf16_f32 v147, v112, v120
	global_store_dwordx4 v179, v[144:147], s[24:25]
	v_cvt_pk_bf16_f32 v148, v65, v73
	v_cvt_pk_bf16_f32 v149, v81, v89
	v_cvt_pk_bf16_f32 v150, v97, v105
	v_cvt_pk_bf16_f32 v151, v113, v121
	s_add_u32 s24, s24, s26
	s_addc_u32 s25, s25, 0
	global_store_dwordx4 v179, v[148:151], s[24:25]
	v_cvt_pk_bf16_f32 v152, v66, v74
	v_cvt_pk_bf16_f32 v153, v82, v90
	v_cvt_pk_bf16_f32 v154, v98, v106
	v_cvt_pk_bf16_f32 v155, v114, v122
	s_add_u32 s24, s24, s26
	s_addc_u32 s25, s25, 0
	global_store_dwordx4 v179, v[152:155], s[24:25]
	v_cvt_pk_bf16_f32 v156, v67, v75
	v_cvt_pk_bf16_f32 v157, v83, v91
	v_cvt_pk_bf16_f32 v158, v99, v107
	v_cvt_pk_bf16_f32 v159, v115, v123
	s_add_u32 s24, s24, s26
	s_addc_u32 s25, s25, 0
	global_store_dwordx4 v179, v[156:159], s[24:25]
	v_cvt_pk_bf16_f32 v160, v68, v76
	v_cvt_pk_bf16_f32 v161, v84, v92
	v_cvt_pk_bf16_f32 v162, v100, v108
	v_cvt_pk_bf16_f32 v163, v116, v124
	s_mul_i32 s2, s26, 29
	s_add_u32 s24, s24, s2
	s_addc_u32 s25, s25, 0
	global_store_dwordx4 v179, v[160:163], s[24:25]
	v_cvt_pk_bf16_f32 v164, v69, v77
	v_cvt_pk_bf16_f32 v165, v85, v93
	v_cvt_pk_bf16_f32 v166, v101, v109
	v_cvt_pk_bf16_f32 v167, v117, v125
	s_add_u32 s24, s24, s26
	s_addc_u32 s25, s25, 0
	global_store_dwordx4 v179, v[164:167], s[24:25]
	v_cvt_pk_bf16_f32 v168, v70, v78
	v_cvt_pk_bf16_f32 v169, v86, v94
	v_cvt_pk_bf16_f32 v170, v102, v110
	v_cvt_pk_bf16_f32 v171, v118, v126
	s_add_u32 s24, s24, s26
	s_addc_u32 s25, s25, 0
	global_store_dwordx4 v179, v[168:171], s[24:25]
	v_cvt_pk_bf16_f32 v172, v71, v79
	v_cvt_pk_bf16_f32 v173, v87, v95
	v_cvt_pk_bf16_f32 v174, v103, v111
	v_cvt_pk_bf16_f32 v175, v119, v127
	s_add_u32 s24, s24, s26
	s_addc_u32 s25, s25, 0
	global_store_dwordx4 v179, v[172:175], s[24:25]
	s_cmp_lt_u32 s4, 0x1600
	s_cbranch_scc1 .Lcv1_lb_go
	s_mov_b32 s28, 0
	s_branch .Lcv1_lb_end

.Lcv1_lb_end:
	s_cmp_eq_u32 s22, 0
	s_cbranch_scc1 .Lcv1_done
	s_cmp_eq_u32 s28, 18
	s_cbranch_scc1 .Lcv1_wa_w18
	s_cmp_eq_u32 s28, 16
	s_cbranch_scc1 .Lcv1_wa_w16
	s_waitcnt vmcnt(8)
	s_branch .Lcv1_wa_wd

.Lcv1_done:
.LBB0_931:
	s_waitcnt vmcnt(0)
	s_waitcnt lgkmcnt(0)
	s_barrier
	s_mov_b64 s[0:1], exec
	v_readlane_b32 s2, v234, 20
	v_readlane_b32 s3, v234, 21
	s_and_b64 s[2:3], s[0:1], s[2:3]
	s_mov_b64 exec, s[2:3]
	s_cbranch_execz .LBB0_990
	s_add_i32 s2, 0, 0x27ff0
	v_mov_b32_e32 v0, s2
	s_waitcnt vmcnt(0) expcnt(0) lgkmcnt(0)
	ds_read_b32 v2, v0
	s_add_i32 s2, 0, 0x27ff4
	v_mov_b32_e32 v0, s2
	ds_read_b32 v0, v0
	s_waitcnt lgkmcnt(1)
	v_cmp_ne_u32_e32 vcc, 0, v2
	s_cbranch_vccnz .LBB0_947
	v_readlane_b32 s2, v234, 12
	v_readlane_b32 s3, v234, 13
	v_readlane_b32 s4, v234, 16
	v_readlane_b32 s36, v234, 0
	s_mul_i32 s33, s3, s4
	v_readlane_b32 s38, v234, 2
	s_mul_i32 s33, s33, s2
	v_readlane_b32 s39, v234, 3
	s_add_u32 s2, s38, 0x100200
	s_addc_u32 s3, s39, 0
	s_add_u32 s4, s38, 0x100400
	s_addc_u32 s5, s39, 0
	s_add_u32 s6, s38, 0x100500
	s_addc_u32 s7, s39, 0
	s_add_u32 s8, s38, 0x100600
	s_addc_u32 s9, s39, 0
	s_add_u32 s12, s38, 0x100700
	s_addc_u32 s13, s39, 0
	s_add_u32 s14, s38, 0x100800
	s_addc_u32 s15, s39, 0
	s_add_u32 s16, s38, 0x100900
	s_addc_u32 s17, s39, 0
	s_add_u32 s18, s38, 0x100a00
	s_addc_u32 s19, s39, 0
	s_add_u32 s20, s38, 0x100b00
	s_addc_u32 s21, s39, 0
	s_add_u32 s22, s38, 0x100c00
	s_addc_u32 s23, s39, 0
	s_add_u32 s24, s38, 0x100d00
	s_addc_u32 s25, s39, 0
	s_add_u32 s26, s38, 0x100e00
	s_addc_u32 s27, s39, 0
	s_add_u32 s28, s38, 0x100f00
	s_addc_u32 s29, s39, 0
	s_add_u32 s30, s38, 0x101000
	s_addc_u32 s31, s39, 0
	s_add_u32 s34, s38, 0x101100
	s_addc_u32 s35, s39, 0
	v_readlane_b32 s37, v234, 1
	s_add_u32 s36, s38, 0x101200
	s_addc_u32 s37, s39, 0
	s_add_u32 s38, s38, 0x101300
	s_addc_u32 s39, s39, 0
	s_mov_b32 s46, 1
	v_mov_b32_e32 v16, 0
	s_branch .LBB0_935

.LBB0_1169:
	s_mul_hi_u32 s0, s53, 0x79b
	s_mul_i32 s0, s0, s52
	s_sub_i32 s0, 0x79b, s0
	s_sub_i32 s1, s0, s52
	s_cmp_ge_u32 s0, s52
	s_cselect_b32 s0, s1, s0
	s_sub_i32 s1, s0, s52
	s_cmp_ge_u32 s0, s52
	s_cselect_b32 s7, s1, s0
	s_cmp_lg_u32 s7, 0
	v_readlane_b32 s2, v234, 14
	s_cselect_b64 s[0:1], -1, 0
	s_cmp_ge_i32 s2, s7
	s_cselect_b64 s[2:3], -1, 0
	s_and_b64 s[0:1], s[0:1], s[2:3]
	s_and_b64 vcc, exec, s[0:1]
	s_cbranch_vccz .LBB0_1605
	v_readlane_b32 s2, v234, 14
	v_readlane_b32 s3, v234, 12
	v_readfirstlane_b32 s0, v183
	s_sub_i32 s2, s2, s7
	s_sub_i32 s3, s3, s7
	s_lshl_b32 s2, s2, 3
	s_lshr_b32 s0, s0, 6
	s_add_i32 s4, s2, s0
	s_lshl_b32 s33, s3, 3
	s_cmp_ge_u32 s4, 0x1a00
	s_cbranch_scc1 .LBB0_1605
	v_readlane_b32 s30, v234, 2
	v_readlane_b32 s31, v234, 3
	v_and_b32_e32 v176, 7, v183
	v_bfe_u32 v185, v183, 3, 3
	v_lshlrev_b32_e32 v177, 4, v185
	v_lshlrev_b32_e32 v186, 4, v176
	v_lshlrev_b32_e32 v184, 5, v176
	s_cmp_lt_u32 s4, 0x1a00
	s_cbranch_scc1 .Lcv2_p0_go
	s_mov_b32 s22, 0
	s_branch .Lcv2_p0_end
.Lcv2_p0_go:
	s_cmp_lt_u32 s4, 0x400
	s_cbranch_scc0 .Lcv2_p0_seg1
	s_sub_u32 s34, s4, 0x0
	s_lshr_b32 s39, s34, 5
	s_and_b32 s40, s34, 31
	v_readlane_b32 s0, v233, 4
	v_readlane_b32 s1, v233, 5
	s_mul_i32 s2, s39, 0x80000
	s_lshl_b32 s3, s40, 8
	s_add_u32 s2, s2, s3
	s_add_u32 s0, s0, s2
	s_addc_u32 s1, s1, 0
	s_mov_b32 s41, 0x2000
	s_mov_b32 s42, 0x10000
	s_mul_i32 s2, s40, 0x40000
	s_lshl_b32 s3, s39, 7
	s_add_u32 s2, s2, s3
	s_add_u32 s2, s2, 0x7f00000
	s_add_u32 s16, s30, s2
	s_addc_u32 s17, s31, 0
	s_mov_b32 s20, 0x1000
	s_mov_b32 s21, 0x4000
	s_mov_b32 s22, 16
	s_branch .Lcv2_p0_ld
.Lcv2_p0_seg1:
	s_cmp_lt_u32 s4, 0xf00
	s_cbranch_scc0 .Lcv2_p0_seg2
	s_sub_u32 s34, s4, 0x400
	s_lshr_b32 s39, s34, 5
	s_and_b32 s40, s34, 31
	v_readlane_b32 s0, v234, 8
	v_readlane_b32 s1, v234, 9
	s_mul_i32 s2, s39, 0x80000
	s_lshl_b32 s3, s40, 8
	s_add_u32 s2, s2, s3
	s_add_u32 s0, s0, s2
	s_addc_u32 s1, s1, 0
	s_mov_b32 s41, 0x2000
	s_mov_b32 s42, 0x10000
	s_mul_i32 s2, s40, 0xb0000
	s_lshl_b32 s3, s39, 7
	s_add_u32 s2, s2, s3
	s_add_u32 s2, s2, 0xb300000
	s_add_u32 s16, s30, s2
	s_addc_u32 s17, s31, 0
	s_mov_b32 s20, 0x2c00
	s_mov_b32 s21, 0xb000
	s_mov_b32 s22, 16
	s_branch .Lcv2_p0_ld
.Lcv2_p0_seg2:
	s_sub_u32 s34, s4, 0xf00
	s_mul_i32 s39, s34, 5958
	s_lshr_b32 s39, s39, 19
	s_mul_i32 s40, s39, 88
	s_sub_u32 s40, s34, s40
	v_readlane_b32 s0, v234, 6
	v_readlane_b32 s1, v234, 7
	s_mul_i32 s2, s39, 0x160000
	s_lshl_b32 s3, s40, 8
	s_add_u32 s2, s2, s3
	s_add_u32 s0, s0, s2
	s_addc_u32 s1, s1, 0
	s_mov_b32 s41, 0x5800
	s_mov_b32 s42, 0x2c000
	s_lshr_b32 s2, s40, 1
	s_lshl_b32 s2, s2, 8
	s_and_b32 s3, s40, 1
	s_lshl_b32 s3, s3, 6
	s_add_u32 s2, s2, s3
	s_add_u32 s2, s2, 0x80
	s_mul_i32 s2, s2, 0x1000
	s_lshl_b32 s3, s39, 7
	s_add_u32 s2, s2, s3
	s_add_u32 s2, s2, 0x8700000
	s_add_u32 s16, s30, s2
	s_addc_u32 s17, s31, 0
	s_mov_b32 s20, 0x1000
	s_mov_b32 s21, 0x4000
	v_readlane_b32 s8, v233, 6
	v_readlane_b32 s9, v233, 7
	s_lshl_b32 s3, s39, 8
	s_mov_b32 s22, 18
	s_nop 0
	s_add_u32 s8, s8, s3
	s_addc_u32 s9, s9, 0

.Lcv2_p0_end:
	s_cmp_lt_u32 s4, 0x1a00
	s_cbranch_scc1 .Lcv2_p1_go
	s_mov_b32 s28, 0
	s_branch .Lcv2_p1_end
.Lcv2_p1_go:
	s_cmp_lt_u32 s4, 0x400
	s_cbranch_scc0 .Lcv2_p1_seg1
	s_sub_u32 s34, s4, 0x0
	s_lshr_b32 s39, s34, 5
	s_and_b32 s40, s34, 31
	v_readlane_b32 s0, v233, 4
	v_readlane_b32 s1, v233, 5
	s_mul_i32 s2, s39, 0x80000
	s_lshl_b32 s3, s40, 8
	s_add_u32 s2, s2, s3
	s_add_u32 s0, s0, s2
	s_addc_u32 s1, s1, 0
	s_mov_b32 s41, 0x2000
	s_mov_b32 s42, 0x10000
	s_mul_i32 s2, s40, 0x40000
	s_lshl_b32 s3, s39, 7
	s_add_u32 s2, s2, s3
	s_add_u32 s2, s2, 0x7f00000
	s_add_u32 s24, s30, s2
	s_addc_u32 s25, s31, 0
	s_mov_b32 s26, 0x1000
	s_mov_b32 s27, 0x4000
	s_mov_b32 s28, 16
	s_branch .Lcv2_p1_ld
.Lcv2_p1_seg1:
	s_cmp_lt_u32 s4, 0xf00
	s_cbranch_scc0 .Lcv2_p1_seg2
	s_sub_u32 s34, s4, 0x400
	s_lshr_b32 s39, s34, 5
	s_and_b32 s40, s34, 31
	v_readlane_b32 s0, v234, 8
	v_readlane_b32 s1, v234, 9
	s_mul_i32 s2, s39, 0x80000
	s_lshl_b32 s3, s40, 8
	s_add_u32 s2, s2, s3
	s_add_u32 s0, s0, s2
	s_addc_u32 s1, s1, 0
	s_mov_b32 s41, 0x2000
	s_mov_b32 s42, 0x10000
	s_mul_i32 s2, s40, 0xb0000
	s_lshl_b32 s3, s39, 7
	s_add_u32 s2, s2, s3
	s_add_u32 s2, s2, 0xb300000
	s_add_u32 s24, s30, s2
	s_addc_u32 s25, s31, 0
	s_mov_b32 s26, 0x2c00
	s_mov_b32 s27, 0xb000
	s_mov_b32 s28, 16
	s_branch .Lcv2_p1_ld
.Lcv2_p1_seg2:
	s_sub_u32 s34, s4, 0xf00
	s_mul_i32 s39, s34, 5958
	s_lshr_b32 s39, s39, 19
	s_mul_i32 s40, s39, 88
	s_sub_u32 s40, s34, s40
	v_readlane_b32 s0, v234, 6
	v_readlane_b32 s1, v234, 7
	s_mul_i32 s2, s39, 0x160000
	s_lshl_b32 s3, s40, 8
	s_add_u32 s2, s2, s3
	s_add_u32 s0, s0, s2
	s_addc_u32 s1, s1, 0
	s_mov_b32 s41, 0x5800
	s_mov_b32 s42, 0x2c000
	s_lshr_b32 s2, s40, 1
	s_lshl_b32 s2, s2, 8
	s_and_b32 s3, s40, 1
	s_lshl_b32 s3, s3, 6
	s_add_u32 s2, s2, s3
	s_add_u32 s2, s2, 0x80
	s_mul_i32 s2, s2, 0x1000
	s_lshl_b32 s3, s39, 7
	s_add_u32 s2, s2, s3
	s_add_u32 s2, s2, 0x8700000
	s_add_u32 s24, s30, s2
	s_addc_u32 s25, s31, 0
	s_mov_b32 s26, 0x1000
	s_mov_b32 s27, 0x4000
	v_readlane_b32 s8, v233, 6
	v_readlane_b32 s9, v233, 7
	s_lshl_b32 s3, s39, 8
	s_mov_b32 s28, 18
	s_nop 0
	s_add_u32 s8, s8, s3
	s_addc_u32 s9, s9, 0

.Lcv2_pw_wd:
.Lcv2_loop:
	v_mad_u32_u24 v179, v185, s21, v186
	v_pk_mul_f32 v[0:1], v[0:1], v[128:129] op_sel_hi:[1,0]
	v_pk_mul_f32 v[2:3], v[2:3], v[128:129] op_sel_hi:[1,0]
	v_pk_mul_f32 v[4:5], v[4:5], v[128:129] op_sel_hi:[1,0]
	v_pk_mul_f32 v[6:7], v[6:7], v[128:129] op_sel_hi:[1,0]
	v_pk_mul_f32 v[8:9], v[8:9], v[128:129] op_sel:[0,1]
	v_pk_mul_f32 v[10:11], v[10:11], v[128:129] op_sel:[0,1]
	v_pk_mul_f32 v[12:13], v[12:13], v[128:129] op_sel:[0,1]
	v_pk_mul_f32 v[14:15], v[14:15], v[128:129] op_sel:[0,1]
	v_pk_mul_f32 v[16:17], v[16:17], v[130:131] op_sel_hi:[1,0]
	v_pk_mul_f32 v[18:19], v[18:19], v[130:131] op_sel_hi:[1,0]
	v_pk_mul_f32 v[20:21], v[20:21], v[130:131] op_sel_hi:[1,0]
	v_pk_mul_f32 v[22:23], v[22:23], v[130:131] op_sel_hi:[1,0]
	v_pk_mul_f32 v[24:25], v[24:25], v[130:131] op_sel:[0,1]
	v_pk_mul_f32 v[26:27], v[26:27], v[130:131] op_sel:[0,1]
	v_pk_mul_f32 v[28:29], v[28:29], v[130:131] op_sel:[0,1]
	v_pk_mul_f32 v[30:31], v[30:31], v[130:131] op_sel:[0,1]
	v_pk_mul_f32 v[32:33], v[32:33], v[132:133] op_sel_hi:[1,0]
	v_pk_mul_f32 v[34:35], v[34:35], v[132:133] op_sel_hi:[1,0]
	v_pk_mul_f32 v[36:37], v[36:37], v[132:133] op_sel_hi:[1,0]
	v_pk_mul_f32 v[38:39], v[38:39], v[132:133] op_sel_hi:[1,0]
	v_pk_mul_f32 v[40:41], v[40:41], v[132:133] op_sel:[0,1]
	v_pk_mul_f32 v[42:43], v[42:43], v[132:133] op_sel:[0,1]
	v_pk_mul_f32 v[44:45], v[44:45], v[132:133] op_sel:[0,1]
	v_pk_mul_f32 v[46:47], v[46:47], v[132:133] op_sel:[0,1]
	v_pk_mul_f32 v[48:49], v[48:49], v[134:135] op_sel_hi:[1,0]
	v_pk_mul_f32 v[50:51], v[50:51], v[134:135] op_sel_hi:[1,0]
	v_pk_mul_f32 v[52:53], v[52:53], v[134:135] op_sel_hi:[1,0]
	v_pk_mul_f32 v[54:55], v[54:55], v[134:135] op_sel_hi:[1,0]
	v_pk_mul_f32 v[56:57], v[56:57], v[134:135] op_sel:[0,1]
	v_pk_mul_f32 v[58:59], v[58:59], v[134:135] op_sel:[0,1]
	v_pk_mul_f32 v[60:61], v[60:61], v[134:135] op_sel:[0,1]
	v_pk_mul_f32 v[62:63], v[62:63], v[134:135] op_sel:[0,1]
	v_cvt_pk_bf16_f32 v144, v0, v8
	v_cvt_pk_bf16_f32 v145, v16, v24
	v_cvt_pk_bf16_f32 v146, v32, v40
	v_cvt_pk_bf16_f32 v147, v48, v56
	global_store_dwordx4 v179, v[144:147], s[16:17]
	v_cvt_pk_bf16_f32 v148, v1, v9
	v_cvt_pk_bf16_f32 v149, v17, v25
	v_cvt_pk_bf16_f32 v150, v33, v41
	v_cvt_pk_bf16_f32 v151, v49, v57
	s_add_u32 s16, s16, s20
	s_addc_u32 s17, s17, 0
	global_store_dwordx4 v179, v[148:151], s[16:17]
	v_cvt_pk_bf16_f32 v152, v2, v10
	v_cvt_pk_bf16_f32 v153, v18, v26
	v_cvt_pk_bf16_f32 v154, v34, v42
	v_cvt_pk_bf16_f32 v155, v50, v58
	s_add_u32 s16, s16, s20
	s_addc_u32 s17, s17, 0
	global_store_dwordx4 v179, v[152:155], s[16:17]
	v_cvt_pk_bf16_f32 v156, v3, v11
	v_cvt_pk_bf16_f32 v157, v19, v27
	v_cvt_pk_bf16_f32 v158, v35, v43
	v_cvt_pk_bf16_f32 v159, v51, v59
	s_add_u32 s16, s16, s20
	s_addc_u32 s17, s17, 0
	global_store_dwordx4 v179, v[156:159], s[16:17]
	v_cvt_pk_bf16_f32 v160, v4, v12
	v_cvt_pk_bf16_f32 v161, v20, v28
	v_cvt_pk_bf16_f32 v162, v36, v44
	v_cvt_pk_bf16_f32 v163, v52, v60
	s_mul_i32 s2, s20, 29
	s_add_u32 s16, s16, s2
	s_addc_u32 s17, s17, 0
	global_store_dwordx4 v179, v[160:163], s[16:17]
	v_cvt_pk_bf16_f32 v164, v5, v13
	v_cvt_pk_bf16_f32 v165, v21, v29
	v_cvt_pk_bf16_f32 v166, v37, v45
	v_cvt_pk_bf16_f32 v167, v53, v61
	s_add_u32 s16, s16, s20
	s_addc_u32 s17, s17, 0
	global_store_dwordx4 v179, v[164:167], s[16:17]
	v_cvt_pk_bf16_f32 v168, v6, v14
	v_cvt_pk_bf16_f32 v169, v22, v30
	v_cvt_pk_bf16_f32 v170, v38, v46
	v_cvt_pk_bf16_f32 v171, v54, v62
	s_add_u32 s16, s16, s20
	s_addc_u32 s17, s17, 0
	global_store_dwordx4 v179, v[168:171], s[16:17]
	v_cvt_pk_bf16_f32 v172, v7, v15
	v_cvt_pk_bf16_f32 v173, v23, v31
	v_cvt_pk_bf16_f32 v174, v39, v47
	v_cvt_pk_bf16_f32 v175, v55, v63
	s_add_u32 s16, s16, s20
	s_addc_u32 s17, s17, 0
	global_store_dwordx4 v179, v[172:175], s[16:17]
	s_cmp_lt_u32 s4, 0x1a00
	s_cbranch_scc1 .Lcv2_la_go
	s_mov_b32 s22, 0
	s_branch .Lcv2_la_end

.Lcv2_wb_wd:
	v_mad_u32_u24 v179, v185, s27, v186
	v_pk_mul_f32 v[64:65], v[64:65], v[136:137] op_sel_hi:[1,0]
	v_pk_mul_f32 v[66:67], v[66:67], v[136:137] op_sel_hi:[1,0]
	v_pk_mul_f32 v[68:69], v[68:69], v[136:137] op_sel_hi:[1,0]
	v_pk_mul_f32 v[70:71], v[70:71], v[136:137] op_sel_hi:[1,0]
	v_pk_mul_f32 v[72:73], v[72:73], v[136:137] op_sel:[0,1]
	v_pk_mul_f32 v[74:75], v[74:75], v[136:137] op_sel:[0,1]
	v_pk_mul_f32 v[76:77], v[76:77], v[136:137] op_sel:[0,1]
	v_pk_mul_f32 v[78:79], v[78:79], v[136:137] op_sel:[0,1]
	v_pk_mul_f32 v[80:81], v[80:81], v[138:139] op_sel_hi:[1,0]
	v_pk_mul_f32 v[82:83], v[82:83], v[138:139] op_sel_hi:[1,0]
	v_pk_mul_f32 v[84:85], v[84:85], v[138:139] op_sel_hi:[1,0]
	v_pk_mul_f32 v[86:87], v[86:87], v[138:139] op_sel_hi:[1,0]
	v_pk_mul_f32 v[88:89], v[88:89], v[138:139] op_sel:[0,1]
	v_pk_mul_f32 v[90:91], v[90:91], v[138:139] op_sel:[0,1]
	v_pk_mul_f32 v[92:93], v[92:93], v[138:139] op_sel:[0,1]
	v_pk_mul_f32 v[94:95], v[94:95], v[138:139] op_sel:[0,1]
	v_pk_mul_f32 v[96:97], v[96:97], v[140:141] op_sel_hi:[1,0]
	v_pk_mul_f32 v[98:99], v[98:99], v[140:141] op_sel_hi:[1,0]
	v_pk_mul_f32 v[100:101], v[100:101], v[140:141] op_sel_hi:[1,0]
	v_pk_mul_f32 v[102:103], v[102:103], v[140:141] op_sel_hi:[1,0]
	v_pk_mul_f32 v[104:105], v[104:105], v[140:141] op_sel:[0,1]
	v_pk_mul_f32 v[106:107], v[106:107], v[140:141] op_sel:[0,1]
	v_pk_mul_f32 v[108:109], v[108:109], v[140:141] op_sel:[0,1]
	v_pk_mul_f32 v[110:111], v[110:111], v[140:141] op_sel:[0,1]
	v_pk_mul_f32 v[112:113], v[112:113], v[142:143] op_sel_hi:[1,0]
	v_pk_mul_f32 v[114:115], v[114:115], v[142:143] op_sel_hi:[1,0]
	v_pk_mul_f32 v[116:117], v[116:117], v[142:143] op_sel_hi:[1,0]
	v_pk_mul_f32 v[118:119], v[118:119], v[142:143] op_sel_hi:[1,0]
	v_pk_mul_f32 v[120:121], v[120:121], v[142:143] op_sel:[0,1]
	v_pk_mul_f32 v[122:123], v[122:123], v[142:143] op_sel:[0,1]
	v_pk_mul_f32 v[124:125], v[124:125], v[142:143] op_sel:[0,1]
	v_pk_mul_f32 v[126:127], v[126:127], v[142:143] op_sel:[0,1]
	v_cvt_pk_bf16_f32 v144, v64, v72
	v_cvt_pk_bf16_f32 v145, v80, v88
	v_cvt_pk_bf16_f32 v146, v96, v104
	v_cvt_pk_bf16_f32 v147, v112, v120
	global_store_dwordx4 v179, v[144:147], s[24:25]
	v_cvt_pk_bf16_f32 v148, v65, v73
	v_cvt_pk_bf16_f32 v149, v81, v89
	v_cvt_pk_bf16_f32 v150, v97, v105
	v_cvt_pk_bf16_f32 v151, v113, v121
	s_add_u32 s24, s24, s26
	s_addc_u32 s25, s25, 0
	global_store_dwordx4 v179, v[148:151], s[24:25]
	v_cvt_pk_bf16_f32 v152, v66, v74
	v_cvt_pk_bf16_f32 v153, v82, v90
	v_cvt_pk_bf16_f32 v154, v98, v106
	v_cvt_pk_bf16_f32 v155, v114, v122
	s_add_u32 s24, s24, s26
	s_addc_u32 s25, s25, 0
	global_store_dwordx4 v179, v[152:155], s[24:25]
	v_cvt_pk_bf16_f32 v156, v67, v75
	v_cvt_pk_bf16_f32 v157, v83, v91
	v_cvt_pk_bf16_f32 v158, v99, v107
	v_cvt_pk_bf16_f32 v159, v115, v123
	s_add_u32 s24, s24, s26
	s_addc_u32 s25, s25, 0
	global_store_dwordx4 v179, v[156:159], s[24:25]
	v_cvt_pk_bf16_f32 v160, v68, v76
	v_cvt_pk_bf16_f32 v161, v84, v92
	v_cvt_pk_bf16_f32 v162, v100, v108
	v_cvt_pk_bf16_f32 v163, v116, v124
	s_mul_i32 s2, s26, 29
	s_add_u32 s24, s24, s2
	s_addc_u32 s25, s25, 0
	global_store_dwordx4 v179, v[160:163], s[24:25]
	v_cvt_pk_bf16_f32 v164, v69, v77
	v_cvt_pk_bf16_f32 v165, v85, v93
	v_cvt_pk_bf16_f32 v166, v101, v109
	v_cvt_pk_bf16_f32 v167, v117, v125
	s_add_u32 s24, s24, s26
	s_addc_u32 s25, s25, 0
	global_store_dwordx4 v179, v[164:167], s[24:25]
	v_cvt_pk_bf16_f32 v168, v70, v78
	v_cvt_pk_bf16_f32 v169, v86, v94
	v_cvt_pk_bf16_f32 v170, v102, v110
	v_cvt_pk_bf16_f32 v171, v118, v126
	s_add_u32 s24, s24, s26
	s_addc_u32 s25, s25, 0
	global_store_dwordx4 v179, v[168:171], s[24:25]
	v_cvt_pk_bf16_f32 v172, v71, v79
	v_cvt_pk_bf16_f32 v173, v87, v95
	v_cvt_pk_bf16_f32 v174, v103, v111
	v_cvt_pk_bf16_f32 v175, v119, v127
	s_add_u32 s24, s24, s26
	s_addc_u32 s25, s25, 0
	global_store_dwordx4 v179, v[172:175], s[24:25]
	s_cmp_lt_u32 s4, 0x1a00
	s_cbranch_scc1 .Lcv2_lb_go
	s_mov_b32 s28, 0
	s_branch .Lcv2_lb_end

.Lcv2_done:
.LBB0_1605:
	s_waitcnt vmcnt(0)
	s_waitcnt lgkmcnt(0)
	s_barrier
	s_mov_b64 s[0:1], exec
	v_readlane_b32 s2, v234, 20
	v_readlane_b32 s3, v234, 21
	s_and_b64 s[2:3], s[0:1], s[2:3]
	s_mov_b64 exec, s[2:3]
	s_cbranch_execz .LBB0_1664
	s_add_i32 s2, 0, 0x27ff0
	v_mov_b32_e32 v0, s2
	s_waitcnt vmcnt(0) expcnt(0) lgkmcnt(0)
	ds_read_b32 v2, v0
	s_add_i32 s2, 0, 0x27ff4
	v_mov_b32_e32 v0, s2
	ds_read_b32 v0, v0
	s_waitcnt lgkmcnt(1)
	v_cmp_ne_u32_e32 vcc, 0, v2
	s_cbranch_vccnz .LBB0_1621
	v_readlane_b32 s2, v234, 12
	v_readlane_b32 s3, v234, 13
	v_readlane_b32 s4, v234, 16
	v_readlane_b32 s36, v234, 0
	s_mul_i32 s33, s3, s4
	v_readlane_b32 s38, v234, 2
	s_mul_i32 s33, s33, s2
	v_readlane_b32 s39, v234, 3
	s_add_u32 s2, s38, 0x100200
	s_addc_u32 s3, s39, 0
	s_add_u32 s4, s38, 0x100400
	s_addc_u32 s5, s39, 0
	s_add_u32 s6, s38, 0x100500
	s_addc_u32 s7, s39, 0
	s_add_u32 s8, s38, 0x100600
	s_addc_u32 s9, s39, 0
	s_add_u32 s10, s38, 0x100700
	s_addc_u32 s11, s39, 0
	s_add_u32 s14, s38, 0x100800
	s_addc_u32 s15, s39, 0
	s_add_u32 s16, s38, 0x100900
	s_addc_u32 s17, s39, 0
	s_add_u32 s18, s38, 0x100a00
	s_addc_u32 s19, s39, 0
	s_add_u32 s20, s38, 0x100b00
	s_addc_u32 s21, s39, 0
	s_add_u32 s22, s38, 0x100c00
	s_addc_u32 s23, s39, 0
	s_add_u32 s24, s38, 0x100d00
	s_addc_u32 s25, s39, 0
	s_add_u32 s26, s38, 0x100e00
	s_addc_u32 s27, s39, 0
	s_add_u32 s28, s38, 0x100f00
	s_addc_u32 s29, s39, 0
	s_add_u32 s30, s38, 0x101000
	s_addc_u32 s31, s39, 0
	s_add_u32 s34, s38, 0x101100
	s_addc_u32 s35, s39, 0
	v_readlane_b32 s37, v234, 1
	s_add_u32 s36, s38, 0x101200
	s_addc_u32 s37, s39, 0
	s_add_u32 s38, s38, 0x101300
	s_addc_u32 s39, s39, 0
	s_mov_b32 s46, 1
	v_mov_b32_e32 v16, 0
	s_branch .LBB0_1609
